# delta_seq chain: output epilogue (norm, silu gate, pack) run as two interleaved row-group streams instead of four serial ones
# baseline (speedup 1.0000x reference)
.Ldq_nopf2:
	ds_read_b128 v[96:99], v171 offset:41984
	ds_read_b128 v[100:103], v171 offset:42000
	ds_read_b128 v[104:107], v171 offset:42016
	ds_read_b128 v[108:111], v171 offset:42032
	s_waitcnt lgkmcnt(0)
	ds_read_b32 v64, v172 offset:0
	ds_read_b32 v65, v172 offset:256
	ds_read_b32 v66, v172 offset:512
	ds_read_b32 v67, v172 offset:768
	ds_read_b32 v68, v172 offset:1024
	ds_read_b32 v69, v172 offset:1280
	ds_read_b32 v70, v172 offset:1536
	ds_read_b32 v71, v172 offset:1792
	ds_read_b32 v72, v172 offset:2048
	ds_read_b32 v73, v172 offset:2304
	ds_read_b32 v74, v172 offset:2560
	ds_read_b32 v75, v172 offset:2816
	ds_read_b32 v76, v172 offset:3072
	ds_read_b32 v77, v172 offset:3328
	ds_read_b32 v78, v172 offset:3584
	v_lshlrev_b32_e32 v32, 16, v96
	v_and_b32_e32 v33, 0xffff0000, v96
	v_lshlrev_b32_e32 v34, 16, v97
	v_and_b32_e32 v35, 0xffff0000, v97
	v_lshlrev_b32_e32 v36, 16, v98
	v_and_b32_e32 v37, 0xffff0000, v98
	v_lshlrev_b32_e32 v38, 16, v99
	v_and_b32_e32 v39, 0xffff0000, v99
	v_lshlrev_b32_e32 v40, 16, v100
	v_and_b32_e32 v41, 0xffff0000, v100
	v_lshlrev_b32_e32 v42, 16, v101
	v_and_b32_e32 v43, 0xffff0000, v101
	v_lshlrev_b32_e32 v44, 16, v102
	v_and_b32_e32 v45, 0xffff0000, v102
	v_lshlrev_b32_e32 v46, 16, v103
	v_and_b32_e32 v47, 0xffff0000, v103
	v_lshlrev_b32_e32 v48, 16, v104
	v_and_b32_e32 v49, 0xffff0000, v104
	v_lshlrev_b32_e32 v50, 16, v105
	v_and_b32_e32 v51, 0xffff0000, v105
	v_lshlrev_b32_e32 v52, 16, v106
	v_and_b32_e32 v53, 0xffff0000, v106
	v_lshlrev_b32_e32 v54, 16, v107
	v_and_b32_e32 v55, 0xffff0000, v107
	v_lshlrev_b32_e32 v56, 16, v108
	v_and_b32_e32 v57, 0xffff0000, v108
	v_lshlrev_b32_e32 v58, 16, v109
	v_and_b32_e32 v59, 0xffff0000, v109
	v_lshlrev_b32_e32 v60, 16, v110
	v_and_b32_e32 v61, 0xffff0000, v110
	v_lshlrev_b32_e32 v62, 16, v111
	v_and_b32_e32 v63, 0xffff0000, v111
	s_waitcnt lgkmcnt(0)
	ds_read_b32 v79, v172 offset:3840
	ds_read_b32 v80, v172 offset:4096
	ds_read_b32 v81, v172 offset:4352
	ds_read_b32 v82, v172 offset:4608
	ds_read_b32 v83, v172 offset:4864
	ds_read_b32 v84, v172 offset:5120
	ds_read_b32 v85, v172 offset:5376
	ds_read_b32 v86, v172 offset:5632
	ds_read_b32 v87, v172 offset:5888
	ds_read_b32 v88, v172 offset:6144
	ds_read_b32 v89, v172 offset:6400
	ds_read_b32 v90, v172 offset:6656
	ds_read_b32 v91, v172 offset:6912
	ds_read_b32 v92, v172 offset:7168
	ds_read_b32 v93, v172 offset:7424
	v_mfma_f32_32x32x2_f32 v[16:31], v32, v64, 0
	v_mfma_f32_32x32x2_f32 v[16:31], v33, v65, v[16:31]
	v_mfma_f32_32x32x2_f32 v[16:31], v34, v66, v[16:31]
	v_mfma_f32_32x32x2_f32 v[16:31], v35, v67, v[16:31]
	v_mfma_f32_32x32x2_f32 v[16:31], v36, v68, v[16:31]
	v_mfma_f32_32x32x2_f32 v[16:31], v37, v69, v[16:31]
	v_mfma_f32_32x32x2_f32 v[16:31], v38, v70, v[16:31]
	v_mfma_f32_32x32x2_f32 v[16:31], v39, v71, v[16:31]
	v_mfma_f32_32x32x2_f32 v[16:31], v40, v72, v[16:31]
	v_mfma_f32_32x32x2_f32 v[16:31], v41, v73, v[16:31]
	v_mfma_f32_32x32x2_f32 v[16:31], v42, v74, v[16:31]
	v_mfma_f32_32x32x2_f32 v[16:31], v43, v75, v[16:31]
	v_mfma_f32_32x32x2_f32 v[16:31], v44, v76, v[16:31]
	v_mfma_f32_32x32x2_f32 v[16:31], v45, v77, v[16:31]
	v_mfma_f32_32x32x2_f32 v[16:31], v46, v78, v[16:31]
	s_waitcnt lgkmcnt(0)
	ds_read_b32 v94, v172 offset:7680
	ds_read_b32 v95, v172 offset:7936
	v_mfma_f32_32x32x2_f32 v[16:31], v47, v79, v[16:31]
	v_mfma_f32_32x32x2_f32 v[16:31], v48, v80, v[16:31]
	v_mfma_f32_32x32x2_f32 v[16:31], v49, v81, v[16:31]
	v_mfma_f32_32x32x2_f32 v[16:31], v50, v82, v[16:31]
	v_mfma_f32_32x32x2_f32 v[16:31], v51, v83, v[16:31]
	v_mfma_f32_32x32x2_f32 v[16:31], v52, v84, v[16:31]
	v_mfma_f32_32x32x2_f32 v[16:31], v53, v85, v[16:31]
	v_mfma_f32_32x32x2_f32 v[16:31], v54, v86, v[16:31]
	v_mfma_f32_32x32x2_f32 v[16:31], v55, v87, v[16:31]
	v_mfma_f32_32x32x2_f32 v[16:31], v56, v88, v[16:31]
	v_mfma_f32_32x32x2_f32 v[16:31], v57, v89, v[16:31]
	v_mfma_f32_32x32x2_f32 v[16:31], v58, v90, v[16:31]
	v_mfma_f32_32x32x2_f32 v[16:31], v59, v91, v[16:31]
	v_mfma_f32_32x32x2_f32 v[16:31], v60, v92, v[16:31]
	v_mfma_f32_32x32x2_f32 v[16:31], v61, v93, v[16:31]
	s_waitcnt lgkmcnt(0)
	v_mfma_f32_32x32x2_f32 v[16:31], v62, v94, v[16:31]
	v_mfma_f32_32x32x2_f32 v[16:31], v63, v95, v[16:31]
	ds_read_b128 v[96:99], v171 offset:51200
	ds_read_b128 v[100:103], v171 offset:51216
	ds_read_b128 v[104:107], v171 offset:51232
	ds_read_b128 v[108:111], v171 offset:51248
	s_waitcnt lgkmcnt(0)
	ds_read_b32 v64, v172 offset:16384
	ds_read_b32 v65, v172 offset:16640
	ds_read_b32 v66, v172 offset:16896
	ds_read_b32 v67, v172 offset:17152
	ds_read_b32 v68, v172 offset:17408
	ds_read_b32 v69, v172 offset:17664
	ds_read_b32 v70, v172 offset:17920
	ds_read_b32 v71, v172 offset:18176
	ds_read_b32 v72, v172 offset:18432
	ds_read_b32 v73, v172 offset:18688
	ds_read_b32 v74, v172 offset:18944
	ds_read_b32 v75, v172 offset:19200
	ds_read_b32 v76, v172 offset:19456
	ds_read_b32 v77, v172 offset:19712
	ds_read_b32 v78, v172 offset:19968
	v_lshlrev_b32_e32 v32, 16, v96
	v_and_b32_e32 v33, 0xffff0000, v96
	v_lshlrev_b32_e32 v34, 16, v97
	v_and_b32_e32 v35, 0xffff0000, v97
	v_lshlrev_b32_e32 v36, 16, v98
	v_and_b32_e32 v37, 0xffff0000, v98
	v_lshlrev_b32_e32 v38, 16, v99
	v_and_b32_e32 v39, 0xffff0000, v99
	v_lshlrev_b32_e32 v40, 16, v100
	v_and_b32_e32 v41, 0xffff0000, v100
	v_lshlrev_b32_e32 v42, 16, v101
	v_and_b32_e32 v43, 0xffff0000, v101
	v_lshlrev_b32_e32 v44, 16, v102
	v_and_b32_e32 v45, 0xffff0000, v102
	v_lshlrev_b32_e32 v46, 16, v103
	v_and_b32_e32 v47, 0xffff0000, v103
	v_lshlrev_b32_e32 v48, 16, v104
	v_and_b32_e32 v49, 0xffff0000, v104
	v_lshlrev_b32_e32 v50, 16, v105
	v_and_b32_e32 v51, 0xffff0000, v105
	v_lshlrev_b32_e32 v52, 16, v106
	v_and_b32_e32 v53, 0xffff0000, v106
	v_lshlrev_b32_e32 v54, 16, v107
	v_and_b32_e32 v55, 0xffff0000, v107
	v_lshlrev_b32_e32 v56, 16, v108
	v_and_b32_e32 v57, 0xffff0000, v108
	v_lshlrev_b32_e32 v58, 16, v109
	v_and_b32_e32 v59, 0xffff0000, v109
	v_lshlrev_b32_e32 v60, 16, v110
	v_and_b32_e32 v61, 0xffff0000, v110
	v_lshlrev_b32_e32 v62, 16, v111
	v_and_b32_e32 v63, 0xffff0000, v111
	s_waitcnt lgkmcnt(0)
	ds_read_b32 v79, v172 offset:20224
	ds_read_b32 v80, v172 offset:20480
	ds_read_b32 v81, v172 offset:20736
	ds_read_b32 v82, v172 offset:20992
	ds_read_b32 v83, v172 offset:21248
	ds_read_b32 v84, v172 offset:21504
	ds_read_b32 v85, v172 offset:21760
	ds_read_b32 v86, v172 offset:22016
	ds_read_b32 v87, v172 offset:22272
	ds_read_b32 v88, v172 offset:22528
	ds_read_b32 v89, v172 offset:22784
	ds_read_b32 v90, v172 offset:23040
	ds_read_b32 v91, v172 offset:23296
	ds_read_b32 v92, v172 offset:23552
	ds_read_b32 v93, v172 offset:23808
	v_mfma_f32_32x32x2_f32 v[16:31], v32, v64, v[16:31]
	v_mfma_f32_32x32x2_f32 v[16:31], v33, v65, v[16:31]
	v_mfma_f32_32x32x2_f32 v[16:31], v34, v66, v[16:31]
	v_mfma_f32_32x32x2_f32 v[16:31], v35, v67, v[16:31]
	v_mfma_f32_32x32x2_f32 v[16:31], v36, v68, v[16:31]
	v_mfma_f32_32x32x2_f32 v[16:31], v37, v69, v[16:31]
	v_mfma_f32_32x32x2_f32 v[16:31], v38, v70, v[16:31]
	v_mfma_f32_32x32x2_f32 v[16:31], v39, v71, v[16:31]
	v_mfma_f32_32x32x2_f32 v[16:31], v40, v72, v[16:31]
	v_mfma_f32_32x32x2_f32 v[16:31], v41, v73, v[16:31]
	v_mfma_f32_32x32x2_f32 v[16:31], v42, v74, v[16:31]
	v_mfma_f32_32x32x2_f32 v[16:31], v43, v75, v[16:31]
	v_mfma_f32_32x32x2_f32 v[16:31], v44, v76, v[16:31]
	v_mfma_f32_32x32x2_f32 v[16:31], v45, v77, v[16:31]
	v_mfma_f32_32x32x2_f32 v[16:31], v46, v78, v[16:31]
	s_waitcnt lgkmcnt(0)
	ds_read_b32 v94, v172 offset:24064
	ds_read_b32 v95, v172 offset:24320
	v_mfma_f32_32x32x2_f32 v[16:31], v47, v79, v[16:31]
	v_mfma_f32_32x32x2_f32 v[16:31], v48, v80, v[16:31]
	v_mfma_f32_32x32x2_f32 v[16:31], v49, v81, v[16:31]
	v_mfma_f32_32x32x2_f32 v[16:31], v50, v82, v[16:31]
	v_mfma_f32_32x32x2_f32 v[16:31], v51, v83, v[16:31]
	v_mfma_f32_32x32x2_f32 v[16:31], v52, v84, v[16:31]
	v_mfma_f32_32x32x2_f32 v[16:31], v53, v85, v[16:31]
	v_mfma_f32_32x32x2_f32 v[16:31], v54, v86, v[16:31]
	v_mfma_f32_32x32x2_f32 v[16:31], v55, v87, v[16:31]
	v_mfma_f32_32x32x2_f32 v[16:31], v56, v88, v[16:31]
	v_mfma_f32_32x32x2_f32 v[16:31], v57, v89, v[16:31]
	v_mfma_f32_32x32x2_f32 v[16:31], v58, v90, v[16:31]
	v_mfma_f32_32x32x2_f32 v[16:31], v59, v91, v[16:31]
	v_mfma_f32_32x32x2_f32 v[16:31], v60, v92, v[16:31]
	v_mfma_f32_32x32x2_f32 v[16:31], v61, v93, v[16:31]
	s_waitcnt lgkmcnt(0)
	v_mfma_f32_32x32x2_f32 v[16:31], v62, v94, v[16:31]
	v_mfma_f32_32x32x2_f32 v[16:31], v63, v95, v[16:31]
	s_waitcnt lgkmcnt(0)
	s_barrier
	s_nop 7
	s_nop 7
	s_nop 3
	ds_write_b32 v173, v16 offset:41984
	ds_write_b32 v173, v17 offset:42240
	ds_write_b32 v173, v18 offset:42496
	ds_write_b32 v173, v19 offset:42752
	ds_write_b32 v173, v20 offset:44032
	ds_write_b32 v173, v21 offset:44288
	ds_write_b32 v173, v22 offset:44544
	ds_write_b32 v173, v23 offset:44800
	ds_write_b32 v173, v24 offset:46080
	ds_write_b32 v173, v25 offset:46336
	ds_write_b32 v173, v26 offset:46592
	ds_write_b32 v173, v27 offset:46848
	ds_write_b32 v173, v28 offset:48128
	ds_write_b32 v173, v29 offset:48384
	ds_write_b32 v173, v30 offset:48640
	ds_write_b32 v173, v31 offset:48896
	ds_read_b128 v[96:99], v171 offset:32768
	ds_read_b128 v[100:103], v171 offset:32784
	ds_read_b128 v[104:107], v171 offset:32800
	ds_read_b128 v[108:111], v171 offset:32816
	s_waitcnt lgkmcnt(0)
	ds_read_b32 v64, v172 offset:16384
	ds_read_b32 v65, v172 offset:16640
	ds_read_b32 v66, v172 offset:16896
	ds_read_b32 v67, v172 offset:17152
	ds_read_b32 v68, v172 offset:17408
	ds_read_b32 v69, v172 offset:17664
	ds_read_b32 v70, v172 offset:17920
	ds_read_b32 v71, v172 offset:18176
	ds_read_b32 v72, v172 offset:18432
	ds_read_b32 v73, v172 offset:18688
	ds_read_b32 v74, v172 offset:18944
	ds_read_b32 v75, v172 offset:19200
	ds_read_b32 v76, v172 offset:19456
	ds_read_b32 v77, v172 offset:19712
	ds_read_b32 v78, v172 offset:19968
	v_lshlrev_b32_e32 v32, 16, v96
	v_and_b32_e32 v33, 0xffff0000, v96
	v_lshlrev_b32_e32 v34, 16, v97
	v_and_b32_e32 v35, 0xffff0000, v97
	v_lshlrev_b32_e32 v36, 16, v98
	v_and_b32_e32 v37, 0xffff0000, v98
	v_lshlrev_b32_e32 v38, 16, v99
	v_and_b32_e32 v39, 0xffff0000, v99
	v_lshlrev_b32_e32 v40, 16, v100
	v_and_b32_e32 v41, 0xffff0000, v100
	v_lshlrev_b32_e32 v42, 16, v101
	v_and_b32_e32 v43, 0xffff0000, v101
	v_lshlrev_b32_e32 v44, 16, v102
	v_and_b32_e32 v45, 0xffff0000, v102
	v_lshlrev_b32_e32 v46, 16, v103
	v_and_b32_e32 v47, 0xffff0000, v103
	v_lshlrev_b32_e32 v48, 16, v104
	v_and_b32_e32 v49, 0xffff0000, v104
	v_lshlrev_b32_e32 v50, 16, v105
	v_and_b32_e32 v51, 0xffff0000, v105
	v_lshlrev_b32_e32 v52, 16, v106
	v_and_b32_e32 v53, 0xffff0000, v106
	v_lshlrev_b32_e32 v54, 16, v107
	v_and_b32_e32 v55, 0xffff0000, v107
	v_lshlrev_b32_e32 v56, 16, v108
	v_and_b32_e32 v57, 0xffff0000, v108
	v_lshlrev_b32_e32 v58, 16, v109
	v_and_b32_e32 v59, 0xffff0000, v109
	v_lshlrev_b32_e32 v60, 16, v110
	v_and_b32_e32 v61, 0xffff0000, v110
	v_lshlrev_b32_e32 v62, 16, v111
	v_and_b32_e32 v63, 0xffff0000, v111
	s_waitcnt lgkmcnt(0)
	ds_read_b32 v79, v172 offset:20224
	ds_read_b32 v80, v172 offset:20480
	ds_read_b32 v81, v172 offset:20736
	ds_read_b32 v82, v172 offset:20992
	ds_read_b32 v83, v172 offset:21248
	ds_read_b32 v84, v172 offset:21504
	ds_read_b32 v85, v172 offset:21760
	ds_read_b32 v86, v172 offset:22016
	ds_read_b32 v87, v172 offset:22272
	ds_read_b32 v88, v172 offset:22528
	ds_read_b32 v89, v172 offset:22784
	ds_read_b32 v90, v172 offset:23040
	ds_read_b32 v91, v172 offset:23296
	ds_read_b32 v92, v172 offset:23552
	ds_read_b32 v93, v172 offset:23808
	v_mfma_f32_32x32x2_f32 v[16:31], v32, v64, 0
	v_mfma_f32_32x32x2_f32 v[16:31], v33, v65, v[16:31]
	v_mfma_f32_32x32x2_f32 v[16:31], v34, v66, v[16:31]
	v_mfma_f32_32x32x2_f32 v[16:31], v35, v67, v[16:31]
	v_mfma_f32_32x32x2_f32 v[16:31], v36, v68, v[16:31]
	v_mfma_f32_32x32x2_f32 v[16:31], v37, v69, v[16:31]
	v_mfma_f32_32x32x2_f32 v[16:31], v38, v70, v[16:31]
	v_mfma_f32_32x32x2_f32 v[16:31], v39, v71, v[16:31]
	v_mfma_f32_32x32x2_f32 v[16:31], v40, v72, v[16:31]
	v_mfma_f32_32x32x2_f32 v[16:31], v41, v73, v[16:31]
	v_mfma_f32_32x32x2_f32 v[16:31], v42, v74, v[16:31]
	v_mfma_f32_32x32x2_f32 v[16:31], v43, v75, v[16:31]
	v_mfma_f32_32x32x2_f32 v[16:31], v44, v76, v[16:31]
	v_mfma_f32_32x32x2_f32 v[16:31], v45, v77, v[16:31]
	v_mfma_f32_32x32x2_f32 v[16:31], v46, v78, v[16:31]
	s_waitcnt lgkmcnt(0)
	ds_read_b32 v94, v172 offset:24064
	ds_read_b32 v95, v172 offset:24320
	v_mfma_f32_32x32x2_f32 v[16:31], v47, v79, v[16:31]
	v_mfma_f32_32x32x2_f32 v[16:31], v48, v80, v[16:31]
	v_mfma_f32_32x32x2_f32 v[16:31], v49, v81, v[16:31]
	v_mfma_f32_32x32x2_f32 v[16:31], v50, v82, v[16:31]
	v_mfma_f32_32x32x2_f32 v[16:31], v51, v83, v[16:31]
	v_mfma_f32_32x32x2_f32 v[16:31], v52, v84, v[16:31]
	v_mfma_f32_32x32x2_f32 v[16:31], v53, v85, v[16:31]
	v_mfma_f32_32x32x2_f32 v[16:31], v54, v86, v[16:31]
	v_mfma_f32_32x32x2_f32 v[16:31], v55, v87, v[16:31]
	v_mfma_f32_32x32x2_f32 v[16:31], v56, v88, v[16:31]
	v_mfma_f32_32x32x2_f32 v[16:31], v57, v89, v[16:31]
	v_mfma_f32_32x32x2_f32 v[16:31], v58, v90, v[16:31]
	v_mfma_f32_32x32x2_f32 v[16:31], v59, v91, v[16:31]
	v_mfma_f32_32x32x2_f32 v[16:31], v60, v92, v[16:31]
	v_mfma_f32_32x32x2_f32 v[16:31], v61, v93, v[16:31]
	s_waitcnt lgkmcnt(0)
	v_mfma_f32_32x32x2_f32 v[16:31], v62, v94, v[16:31]
	v_mfma_f32_32x32x2_f32 v[16:31], v63, v95, v[16:31]
	s_nop 7
	s_nop 7
	s_nop 3
	v_fma_f32 v0, v164, v0, v16
	v_fma_f32 v1, v164, v1, v17
	v_fma_f32 v2, v164, v2, v18
	v_fma_f32 v3, v164, v3, v19
	v_fma_f32 v4, v164, v4, v20
	v_fma_f32 v5, v164, v5, v21
	v_fma_f32 v6, v164, v6, v22
	v_fma_f32 v7, v164, v7, v23
	v_fma_f32 v8, v164, v8, v24
	v_fma_f32 v9, v164, v9, v25
	v_fma_f32 v10, v164, v10, v26
	v_fma_f32 v11, v164, v11, v27
	v_fma_f32 v12, v164, v12, v28
	v_fma_f32 v13, v164, v13, v29
	v_fma_f32 v14, v164, v14, v30
	v_fma_f32 v15, v164, v15, v31
	ds_write_b32 v173, v0 offset:0
	ds_write_b32 v173, v1 offset:256
	ds_write_b32 v173, v2 offset:512
	ds_write_b32 v173, v3 offset:768
	ds_write_b32 v173, v4 offset:2048
	ds_write_b32 v173, v5 offset:2304
	ds_write_b32 v173, v6 offset:2560
	ds_write_b32 v173, v7 offset:2816
	ds_write_b32 v173, v8 offset:4096
	ds_write_b32 v173, v9 offset:4352
	ds_write_b32 v173, v10 offset:4608
	ds_write_b32 v173, v11 offset:4864
	ds_write_b32 v173, v12 offset:6144
	ds_write_b32 v173, v13 offset:6400
	ds_write_b32 v173, v14 offset:6656
	ds_write_b32 v173, v15 offset:6912
	s_waitcnt lgkmcnt(0)
	s_barrier
	s_cmp_eq_u32 s12, 0
	s_cbranch_scc1 .Ldq_epi3
	ds_read_b128 v[32:35], v175 offset:41984
	s_nop 0
	s_waitcnt lgkmcnt(0)
	s_nop 0
	v_mul_f32_e32 v185, v32, v32
	s_nop 0
	v_fmac_f32_e32 v185, v33, v33
	s_nop 0
	v_fmac_f32_e32 v185, v34, v34
	s_nop 0
	v_fmac_f32_e32 v185, v35, v35
	s_nop 0
	s_nop 1
	s_nop 0
	v_add_f32_dpp v185, v185, v185 quad_perm:[1,0,3,2] row_mask:0xf bank_mask:0xf
	s_nop 0
	s_nop 1
	ds_read_b128 v[36:39], v175 offset:46080
	v_add_f32_dpp v185, v185, v185 quad_perm:[2,3,0,1] row_mask:0xf bank_mask:0xf
	s_waitcnt lgkmcnt(0)
	s_nop 1
	v_mul_f32_e32 v64, v36, v36
	v_add_f32_dpp v185, v185, v185 row_half_mirror row_mask:0xf bank_mask:0xf
	v_fmac_f32_e32 v64, v37, v37
	s_nop 1
	v_fmac_f32_e32 v64, v38, v38
	v_add_f32_dpp v185, v185, v185 row_mirror row_mask:0xf bank_mask:0xf
	v_fmac_f32_e32 v64, v39, v39
	v_mov_b32_e32 v186, 0x358637bd
	s_nop 1
	v_fmac_f32_e32 v186, 0x3c800000, v185
	v_add_f32_dpp v64, v64, v64 quad_perm:[1,0,3,2] row_mask:0xf bank_mask:0xf
	v_rsq_f32_e32 v186, v186
	s_nop 1
	s_nop 0
	v_add_f32_dpp v64, v64, v64 quad_perm:[2,3,0,1] row_mask:0xf bank_mask:0xf
	v_mul_f32_e32 v32, v32, v186
	s_nop 1
	v_mul_f32_e32 v33, v33, v186
	v_add_f32_dpp v64, v64, v64 row_half_mirror row_mask:0xf bank_mask:0xf
	v_mul_f32_e32 v34, v34, v186
	s_nop 1
	v_mul_f32_e32 v35, v35, v186
	v_add_f32_dpp v64, v64, v64 row_mirror row_mask:0xf bank_mask:0xf
	v_mul_f32_e32 v32, v32, v160
	v_mov_b32_e32 v65, 0x358637bd
	v_mul_f32_e32 v33, v33, v161
	v_fmac_f32_e32 v65, 0x3c800000, v64
	v_mul_f32_e32 v34, v34, v162
	v_rsq_f32_e32 v65, v65
	v_mul_f32_e32 v35, v35, v163
	s_nop 0
	v_lshlrev_b32_e32 v187, 16, v152
	v_mul_f32_e32 v36, v36, v65
	v_and_b32_e32 v188, 0xffff0000, v152
	v_mul_f32_e32 v37, v37, v65
	v_lshlrev_b32_e32 v189, 16, v153
	v_mul_f32_e32 v38, v38, v65
	v_and_b32_e32 v190, 0xffff0000, v153
	v_mul_f32_e32 v39, v39, v65
	v_mul_f32_e32 v195, 0xbfb8aa3b, v187
	v_mul_f32_e32 v36, v36, v160
	v_exp_f32_e32 v195, v195
	v_mul_f32_e32 v37, v37, v161
	s_nop 0
	v_mul_f32_e32 v38, v38, v162
	v_add_f32_e32 v195, 1.0, v195
	v_mul_f32_e32 v39, v39, v163
	v_div_scale_f32 v191, s[52:53], v195, v195, v187
	v_lshlrev_b32_e32 v66, 16, v154
	v_rcp_f32_e32 v192, v191
	v_and_b32_e32 v67, 0xffff0000, v154
	s_nop 0
	v_lshlrev_b32_e32 v68, 16, v155
	v_fma_f32 v193, -v191, v192, 1.0
	v_and_b32_e32 v69, 0xffff0000, v155
	v_fmac_f32_e32 v192, v193, v192
	v_mul_f32_e32 v74, 0xbfb8aa3b, v66
	v_div_scale_f32 v193, vcc, v187, v195, v187
	v_exp_f32_e32 v74, v74
	v_mul_f32_e32 v194, v193, v192
	s_nop 0
	v_fma_f32 v196, -v191, v194, v193
	v_add_f32_e32 v74, 1.0, v74
	v_fmac_f32_e32 v194, v196, v192
	v_div_scale_f32 v70, s[52:53], v74, v74, v66
	v_fma_f32 v191, -v191, v194, v193
	v_rcp_f32_e32 v71, v70
	v_div_fmas_f32 v191, v191, v192, v194
	s_nop 0
	v_div_fixup_f32 v191, v191, v195, v187
	v_fma_f32 v72, -v70, v71, 1.0
	v_mul_f32_e32 v32, v32, v191
	v_fmac_f32_e32 v71, v72, v71
	v_mul_f32_e32 v195, 0xbfb8aa3b, v188
	v_div_scale_f32 v72, vcc, v66, v74, v66
	v_exp_f32_e32 v195, v195
	v_mul_f32_e32 v73, v72, v71
	s_nop 0
	v_fma_f32 v75, -v70, v73, v72
	v_add_f32_e32 v195, 1.0, v195
	v_fmac_f32_e32 v73, v75, v71
	v_div_scale_f32 v191, s[52:53], v195, v195, v188
	v_fma_f32 v70, -v70, v73, v72
	v_rcp_f32_e32 v192, v191
	v_div_fmas_f32 v70, v70, v71, v73
	s_nop 0
	v_div_fixup_f32 v70, v70, v74, v66
	v_fma_f32 v193, -v191, v192, 1.0
	v_mul_f32_e32 v36, v36, v70
	v_fmac_f32_e32 v192, v193, v192
	v_mul_f32_e32 v74, 0xbfb8aa3b, v67
	v_div_scale_f32 v193, vcc, v188, v195, v188
	v_exp_f32_e32 v74, v74
	v_mul_f32_e32 v194, v193, v192
	s_nop 0
	v_fma_f32 v196, -v191, v194, v193
	v_add_f32_e32 v74, 1.0, v74
	v_fmac_f32_e32 v194, v196, v192
	v_div_scale_f32 v70, s[52:53], v74, v74, v67
	v_fma_f32 v191, -v191, v194, v193
	v_rcp_f32_e32 v71, v70
	v_div_fmas_f32 v191, v191, v192, v194
	s_nop 0
	v_div_fixup_f32 v191, v191, v195, v188
	v_fma_f32 v72, -v70, v71, 1.0
	v_mul_f32_e32 v33, v33, v191
	v_fmac_f32_e32 v71, v72, v71
	v_mul_f32_e32 v195, 0xbfb8aa3b, v189
	v_div_scale_f32 v72, vcc, v67, v74, v67
	v_exp_f32_e32 v195, v195
	v_mul_f32_e32 v73, v72, v71
	s_nop 0
	v_fma_f32 v75, -v70, v73, v72
	v_add_f32_e32 v195, 1.0, v195
	v_fmac_f32_e32 v73, v75, v71
	v_div_scale_f32 v191, s[52:53], v195, v195, v189
	v_fma_f32 v70, -v70, v73, v72
	v_rcp_f32_e32 v192, v191
	v_div_fmas_f32 v70, v70, v71, v73
	s_nop 0
	v_div_fixup_f32 v70, v70, v74, v67
	v_fma_f32 v193, -v191, v192, 1.0
	v_mul_f32_e32 v37, v37, v70
	v_fmac_f32_e32 v192, v193, v192
	v_mul_f32_e32 v74, 0xbfb8aa3b, v68
	v_div_scale_f32 v193, vcc, v189, v195, v189
	v_exp_f32_e32 v74, v74
	v_mul_f32_e32 v194, v193, v192
	s_nop 0
	v_fma_f32 v196, -v191, v194, v193
	v_add_f32_e32 v74, 1.0, v74
	v_fmac_f32_e32 v194, v196, v192
	v_div_scale_f32 v70, s[52:53], v74, v74, v68
	v_fma_f32 v191, -v191, v194, v193
	v_rcp_f32_e32 v71, v70
	v_div_fmas_f32 v191, v191, v192, v194
	s_nop 0
	v_div_fixup_f32 v191, v191, v195, v189
	v_fma_f32 v72, -v70, v71, 1.0
	v_mul_f32_e32 v34, v34, v191
	v_fmac_f32_e32 v71, v72, v71
	v_mul_f32_e32 v195, 0xbfb8aa3b, v190
	v_div_scale_f32 v72, vcc, v68, v74, v68
	v_exp_f32_e32 v195, v195
	v_mul_f32_e32 v73, v72, v71
	s_nop 0
	v_fma_f32 v75, -v70, v73, v72
	v_add_f32_e32 v195, 1.0, v195
	v_fmac_f32_e32 v73, v75, v71
	v_div_scale_f32 v191, s[52:53], v195, v195, v190
	v_fma_f32 v70, -v70, v73, v72
	v_rcp_f32_e32 v192, v191
	v_div_fmas_f32 v70, v70, v71, v73
	s_nop 0
	v_div_fixup_f32 v70, v70, v74, v68
	v_fma_f32 v193, -v191, v192, 1.0
	v_mul_f32_e32 v38, v38, v70
	v_fmac_f32_e32 v192, v193, v192
	v_mul_f32_e32 v74, 0xbfb8aa3b, v69
	v_div_scale_f32 v193, vcc, v190, v195, v190
	v_exp_f32_e32 v74, v74
	v_mul_f32_e32 v194, v193, v192
	s_nop 0
	v_fma_f32 v196, -v191, v194, v193
	v_add_f32_e32 v74, 1.0, v74
	v_fmac_f32_e32 v194, v196, v192
	v_div_scale_f32 v70, s[52:53], v74, v74, v69
	v_fma_f32 v191, -v191, v194, v193
	v_rcp_f32_e32 v71, v70
	v_div_fmas_f32 v191, v191, v192, v194
	s_nop 0
	v_div_fixup_f32 v191, v191, v195, v190
	v_fma_f32 v72, -v70, v71, 1.0
	v_mul_f32_e32 v35, v35, v191
	v_fmac_f32_e32 v71, v72, v71
	v_bfe_u32 v191, v32, 16, 1
	v_div_scale_f32 v72, vcc, v69, v74, v69
	v_bfe_u32 v192, v33, 16, 1
	v_mul_f32_e32 v73, v72, v71
	v_bfe_u32 v193, v34, 16, 1
	v_fma_f32 v75, -v70, v73, v72
	v_bfe_u32 v194, v35, 16, 1
	v_fmac_f32_e32 v73, v75, v71
	v_add3_u32 v32, v32, v191, s69
	v_fma_f32 v70, -v70, v73, v72
	v_add3_u32 v33, v33, v192, s69
	v_div_fmas_f32 v70, v70, v71, v73
	v_add3_u32 v34, v34, v193, s69
	v_div_fixup_f32 v70, v70, v74, v69
	v_add3_u32 v35, v35, v194, s69
	v_mul_f32_e32 v39, v39, v70
	v_lshrrev_b32_e32 v32, 16, v32
	v_bfe_u32 v70, v36, 16, 1
	v_lshrrev_b32_e32 v34, 16, v34
	v_bfe_u32 v71, v37, 16, 1
	v_and_or_b32 v198, v33, s34, v32
	v_bfe_u32 v72, v38, 16, 1
	v_and_or_b32 v199, v35, s34, v34
	v_bfe_u32 v73, v39, 16, 1
	global_store_dwordx2 v176, v[198:199], s[8:9]
	v_add3_u32 v36, v36, v70, s69
	s_nop 1
	v_add3_u32 v37, v37, v71, s69
	v_add3_u32 v38, v38, v72, s69
	s_nop 0
	v_add3_u32 v39, v39, v73, s69
	s_nop 0
	v_lshrrev_b32_e32 v36, 16, v36
	s_nop 0
	v_lshrrev_b32_e32 v38, 16, v38
	s_nop 0
	v_and_or_b32 v76, v37, s34, v36
	s_nop 0
	v_and_or_b32 v77, v39, s34, v38
	s_nop 0
	global_store_dwordx2 v177, v[76:77], s[8:9]
	s_nop 0
	s_nop 1
	s_nop 0
	ds_read_b128 v[40:43], v175 offset:50176
	s_nop 0
	s_waitcnt lgkmcnt(0)
	s_nop 0
	v_mul_f32_e32 v185, v40, v40
	s_nop 0
	v_fmac_f32_e32 v185, v41, v41
	s_nop 0
	v_fmac_f32_e32 v185, v42, v42
	s_nop 0
	v_fmac_f32_e32 v185, v43, v43
	s_nop 0
	s_nop 1
	s_nop 0
	v_add_f32_dpp v185, v185, v185 quad_perm:[1,0,3,2] row_mask:0xf bank_mask:0xf
	s_nop 0
	s_nop 1
	ds_read_b128 v[44:47], v175 offset:54272
	v_add_f32_dpp v185, v185, v185 quad_perm:[2,3,0,1] row_mask:0xf bank_mask:0xf
	s_waitcnt lgkmcnt(0)
	s_nop 1
	v_mul_f32_e32 v64, v44, v44
	v_add_f32_dpp v185, v185, v185 row_half_mirror row_mask:0xf bank_mask:0xf
	v_fmac_f32_e32 v64, v45, v45
	s_nop 1
	v_fmac_f32_e32 v64, v46, v46
	v_add_f32_dpp v185, v185, v185 row_mirror row_mask:0xf bank_mask:0xf
	v_fmac_f32_e32 v64, v47, v47
	v_mov_b32_e32 v186, 0x358637bd
	s_nop 1
	v_fmac_f32_e32 v186, 0x3c800000, v185
	v_add_f32_dpp v64, v64, v64 quad_perm:[1,0,3,2] row_mask:0xf bank_mask:0xf
	v_rsq_f32_e32 v186, v186
	s_nop 1
	s_nop 0
	v_add_f32_dpp v64, v64, v64 quad_perm:[2,3,0,1] row_mask:0xf bank_mask:0xf
	v_mul_f32_e32 v40, v40, v186
	s_nop 1
	v_mul_f32_e32 v41, v41, v186
	v_add_f32_dpp v64, v64, v64 row_half_mirror row_mask:0xf bank_mask:0xf
	v_mul_f32_e32 v42, v42, v186
	s_nop 1
	v_mul_f32_e32 v43, v43, v186
	v_add_f32_dpp v64, v64, v64 row_mirror row_mask:0xf bank_mask:0xf
	v_mul_f32_e32 v40, v40, v160
	v_mov_b32_e32 v65, 0x358637bd
	v_mul_f32_e32 v41, v41, v161
	v_fmac_f32_e32 v65, 0x3c800000, v64
	v_mul_f32_e32 v42, v42, v162
	v_rsq_f32_e32 v65, v65
	v_mul_f32_e32 v43, v43, v163
	s_nop 0
	v_lshlrev_b32_e32 v187, 16, v156
	v_mul_f32_e32 v44, v44, v65
	v_and_b32_e32 v188, 0xffff0000, v156
	v_mul_f32_e32 v45, v45, v65
	v_lshlrev_b32_e32 v189, 16, v157
	v_mul_f32_e32 v46, v46, v65
	v_and_b32_e32 v190, 0xffff0000, v157
	v_mul_f32_e32 v47, v47, v65
	v_mul_f32_e32 v195, 0xbfb8aa3b, v187
	v_mul_f32_e32 v44, v44, v160
	v_exp_f32_e32 v195, v195
	v_mul_f32_e32 v45, v45, v161
	s_nop 0
	v_mul_f32_e32 v46, v46, v162
	v_add_f32_e32 v195, 1.0, v195
	v_mul_f32_e32 v47, v47, v163
	v_div_scale_f32 v191, s[52:53], v195, v195, v187
	v_lshlrev_b32_e32 v66, 16, v158
	v_rcp_f32_e32 v192, v191
	v_and_b32_e32 v67, 0xffff0000, v158
	s_nop 0
	v_lshlrev_b32_e32 v68, 16, v159
	v_fma_f32 v193, -v191, v192, 1.0
	v_and_b32_e32 v69, 0xffff0000, v159
	v_fmac_f32_e32 v192, v193, v192
	v_mul_f32_e32 v74, 0xbfb8aa3b, v66
	v_div_scale_f32 v193, vcc, v187, v195, v187
	v_exp_f32_e32 v74, v74
	v_mul_f32_e32 v194, v193, v192
	s_nop 0
	v_fma_f32 v196, -v191, v194, v193
	v_add_f32_e32 v74, 1.0, v74
	v_fmac_f32_e32 v194, v196, v192
	v_div_scale_f32 v70, s[52:53], v74, v74, v66
	v_fma_f32 v191, -v191, v194, v193
	v_rcp_f32_e32 v71, v70
	v_div_fmas_f32 v191, v191, v192, v194
	s_nop 0
	v_div_fixup_f32 v191, v191, v195, v187
	v_fma_f32 v72, -v70, v71, 1.0
	v_mul_f32_e32 v40, v40, v191
	v_fmac_f32_e32 v71, v72, v71
	v_mul_f32_e32 v195, 0xbfb8aa3b, v188
	v_div_scale_f32 v72, vcc, v66, v74, v66
	v_exp_f32_e32 v195, v195
	v_mul_f32_e32 v73, v72, v71
	s_nop 0
	v_fma_f32 v75, -v70, v73, v72
	v_add_f32_e32 v195, 1.0, v195
	v_fmac_f32_e32 v73, v75, v71
	v_div_scale_f32 v191, s[52:53], v195, v195, v188
	v_fma_f32 v70, -v70, v73, v72
	v_rcp_f32_e32 v192, v191
	v_div_fmas_f32 v70, v70, v71, v73
	s_nop 0
	v_div_fixup_f32 v70, v70, v74, v66
	v_fma_f32 v193, -v191, v192, 1.0
	v_mul_f32_e32 v44, v44, v70
	v_fmac_f32_e32 v192, v193, v192
	v_mul_f32_e32 v74, 0xbfb8aa3b, v67
	v_div_scale_f32 v193, vcc, v188, v195, v188
	v_exp_f32_e32 v74, v74
	v_mul_f32_e32 v194, v193, v192
	s_nop 0
	v_fma_f32 v196, -v191, v194, v193
	v_add_f32_e32 v74, 1.0, v74
	v_fmac_f32_e32 v194, v196, v192
	v_div_scale_f32 v70, s[52:53], v74, v74, v67
	v_fma_f32 v191, -v191, v194, v193
	v_rcp_f32_e32 v71, v70
	v_div_fmas_f32 v191, v191, v192, v194
	s_nop 0
	v_div_fixup_f32 v191, v191, v195, v188
	v_fma_f32 v72, -v70, v71, 1.0
	v_mul_f32_e32 v41, v41, v191
	v_fmac_f32_e32 v71, v72, v71
	v_mul_f32_e32 v195, 0xbfb8aa3b, v189
	v_div_scale_f32 v72, vcc, v67, v74, v67
	v_exp_f32_e32 v195, v195
	v_mul_f32_e32 v73, v72, v71
	s_nop 0
	v_fma_f32 v75, -v70, v73, v72
	v_add_f32_e32 v195, 1.0, v195
	v_fmac_f32_e32 v73, v75, v71
	v_div_scale_f32 v191, s[52:53], v195, v195, v189
	v_fma_f32 v70, -v70, v73, v72
	v_rcp_f32_e32 v192, v191
	v_div_fmas_f32 v70, v70, v71, v73
	s_nop 0
	v_div_fixup_f32 v70, v70, v74, v67
	v_fma_f32 v193, -v191, v192, 1.0
	v_mul_f32_e32 v45, v45, v70
	v_fmac_f32_e32 v192, v193, v192
	v_mul_f32_e32 v74, 0xbfb8aa3b, v68
	v_div_scale_f32 v193, vcc, v189, v195, v189
	v_exp_f32_e32 v74, v74
	v_mul_f32_e32 v194, v193, v192
	s_nop 0
	v_fma_f32 v196, -v191, v194, v193
	v_add_f32_e32 v74, 1.0, v74
	v_fmac_f32_e32 v194, v196, v192
	v_div_scale_f32 v70, s[52:53], v74, v74, v68
	v_fma_f32 v191, -v191, v194, v193
	v_rcp_f32_e32 v71, v70
	v_div_fmas_f32 v191, v191, v192, v194
	s_nop 0
	v_div_fixup_f32 v191, v191, v195, v189
	v_fma_f32 v72, -v70, v71, 1.0
	v_mul_f32_e32 v42, v42, v191
	v_fmac_f32_e32 v71, v72, v71
	v_mul_f32_e32 v195, 0xbfb8aa3b, v190
	v_div_scale_f32 v72, vcc, v68, v74, v68
	v_exp_f32_e32 v195, v195
	v_mul_f32_e32 v73, v72, v71
	s_nop 0
	v_fma_f32 v75, -v70, v73, v72
	v_add_f32_e32 v195, 1.0, v195
	v_fmac_f32_e32 v73, v75, v71
	v_div_scale_f32 v191, s[52:53], v195, v195, v190
	v_fma_f32 v70, -v70, v73, v72
	v_rcp_f32_e32 v192, v191
	v_div_fmas_f32 v70, v70, v71, v73
	s_nop 0
	v_div_fixup_f32 v70, v70, v74, v68
	v_fma_f32 v193, -v191, v192, 1.0
	v_mul_f32_e32 v46, v46, v70
	v_fmac_f32_e32 v192, v193, v192
	v_mul_f32_e32 v74, 0xbfb8aa3b, v69
	v_div_scale_f32 v193, vcc, v190, v195, v190
	v_exp_f32_e32 v74, v74
	v_mul_f32_e32 v194, v193, v192
	s_nop 0
	v_fma_f32 v196, -v191, v194, v193
	v_add_f32_e32 v74, 1.0, v74
	v_fmac_f32_e32 v194, v196, v192
	v_div_scale_f32 v70, s[52:53], v74, v74, v69
	v_fma_f32 v191, -v191, v194, v193
	v_rcp_f32_e32 v71, v70
	v_div_fmas_f32 v191, v191, v192, v194
	s_nop 0
	v_div_fixup_f32 v191, v191, v195, v190
	v_fma_f32 v72, -v70, v71, 1.0
	v_mul_f32_e32 v43, v43, v191
	v_fmac_f32_e32 v71, v72, v71
	v_bfe_u32 v191, v40, 16, 1
	v_div_scale_f32 v72, vcc, v69, v74, v69
	v_bfe_u32 v192, v41, 16, 1
	v_mul_f32_e32 v73, v72, v71
	v_bfe_u32 v193, v42, 16, 1
	v_fma_f32 v75, -v70, v73, v72
	v_bfe_u32 v194, v43, 16, 1
	v_fmac_f32_e32 v73, v75, v71
	v_add3_u32 v40, v40, v191, s69
	v_fma_f32 v70, -v70, v73, v72
	v_add3_u32 v41, v41, v192, s69
	v_div_fmas_f32 v70, v70, v71, v73
	v_add3_u32 v42, v42, v193, s69
	v_div_fixup_f32 v70, v70, v74, v69
	v_add3_u32 v43, v43, v194, s69
	v_mul_f32_e32 v47, v47, v70
	v_lshrrev_b32_e32 v40, 16, v40
	v_bfe_u32 v70, v44, 16, 1
	v_lshrrev_b32_e32 v42, 16, v42
	v_bfe_u32 v71, v45, 16, 1
	v_and_or_b32 v198, v41, s34, v40
	v_bfe_u32 v72, v46, 16, 1
	v_and_or_b32 v199, v43, s34, v42
	v_bfe_u32 v73, v47, 16, 1
	global_store_dwordx2 v178, v[198:199], s[8:9]
	v_add3_u32 v44, v44, v70, s69
	s_nop 1
	v_add3_u32 v45, v45, v71, s69
	v_add3_u32 v46, v46, v72, s69
	s_nop 0
	v_add3_u32 v47, v47, v73, s69
	s_nop 0
	v_lshrrev_b32_e32 v44, 16, v44
	s_nop 0
	v_lshrrev_b32_e32 v46, 16, v46
	s_nop 0
	v_and_or_b32 v76, v45, s34, v44
	s_nop 0
	v_and_or_b32 v77, v47, s34, v46
	s_nop 0
	global_store_dwordx2 v179, v[76:77], s[8:9]
	s_nop 0
	s_nop 1
	s_nop 0
	s_waitcnt vmcnt(4)
	s_branch .Ldq_epid
